# phase0 x->bf16 copy unrolled x4 (8 loads in flight); attention softmax rescales only when row max grows >4 log2 units
# speedup vs baseline: 1.0042x; 1.0042x over previous
; __device__ __forceinline__ u32x4 pack8(const f32x4 a, const f32x4 b) { u32x4 w; w.x = cvt_pk_bf16(a[0], a[1]); w.y = cvt_pk_bf16(a[2], a[3]); w.z = cvt_pk_bf16(b[0], b[1]); w.w = cvt_pk_bf16(b[2], b[3]); return w; }
;     ...
;             for (int i = gt; i < T * DM / 8; i += NGT) {
;                 const f32x4 a = *(const f32x4*)(p.in[I_X] + (size_t)i * 8), b = *(const f32x4*)(p.in[I_X] + (size_t)i * 8 + 4);
;                 *(u32x4*)(XB + (size_t)i * 8) = pack8(a, b);
;             }
.LBB0_101:
	v_lshl_add_u32 v2, s2, 9, v0
	s_mov_b32 s4, 0x400000
	s_lshl_b32 s6, s34, 9
	v_cmp_gt_i32_e32 vcc, s4, v2
	s_and_saveexec_b64 s[4:5], vcc
	s_cbranch_execz .LBB0_104
	s_load_dwordx2 s[10:11], s[16:17], 0x0
	v_ashrrev_i32_e32 v3, 31, v2
	v_lshlrev_b64 v[6:7], 5, v[2:3]
	s_waitcnt lgkmcnt(0)
	v_lshl_add_u64 v[4:5], v[2:3], 4, s[14:15]
	s_mov_b64 s[8:9], 0x6e30000
	s_ashr_i32 s7, s6, 31
	v_lshl_add_u64 v[6:7], s[10:11], 0, v[6:7]
	v_lshl_add_u64 v[4:5], v[4:5], 0, s[8:9]
	s_lshl_b64 s[8:9], s[6:7], 4
	v_lshl_add_u64 v[6:7], v[6:7], 0, 16
	s_lshl_b64 s[10:11], s[6:7], 5
	s_mov_b64 s[18:19], 0
	s_mov_b32 s7, 0x3fffff
	v_mov_b32_e32 v1, v2
	s_mul_i32 s76, s6, 3
	s_lshl_b32 s78, s6, 2
.Lxc4_head:
	s_nop 0
	v_readfirstlane_b32 s77, v1
	s_add_i32 s79, s77, s76
	s_cmp_lt_i32 s79, 0x400000
	s_cbranch_scc1 .Lxc4_body
	s_cmp_lt_i32 s77, 0x400000
	s_cbranch_scc1 .LBB0_103
	s_branch .LBB0_104
.Lxc4_body:
	global_load_dwordx4 v[100:103], v[6:7], off offset:-16
	global_load_dwordx4 v[104:107], v[6:7], off
	v_lshl_add_u64 v[132:133], v[6:7], 0, s[10:11]
	global_load_dwordx4 v[108:111], v[132:133], off offset:-16
	global_load_dwordx4 v[112:115], v[132:133], off
	v_lshl_add_u64 v[132:133], v[132:133], 0, s[10:11]
	global_load_dwordx4 v[116:119], v[132:133], off offset:-16
	global_load_dwordx4 v[120:123], v[132:133], off
	v_lshl_add_u64 v[132:133], v[132:133], 0, s[10:11]
	global_load_dwordx4 v[124:127], v[132:133], off offset:-16
	global_load_dwordx4 v[128:131], v[132:133], off
	v_lshl_add_u64 v[6:7], v[132:133], 0, s[10:11]
	v_add_u32_e32 v1, s78, v1
	s_waitcnt vmcnt(6)
	v_cvt_pk_bf16_f32 v100, v100, v101
	v_cvt_pk_bf16_f32 v101, v102, v103
	v_cvt_pk_bf16_f32 v102, v104, v105
	v_cvt_pk_bf16_f32 v103, v106, v107
	global_store_dwordx4 v[4:5], v[100:103], off
	v_lshl_add_u64 v[4:5], v[4:5], 0, s[8:9]
	s_waitcnt vmcnt(5)
	v_cvt_pk_bf16_f32 v108, v108, v109
	v_cvt_pk_bf16_f32 v109, v110, v111
	v_cvt_pk_bf16_f32 v110, v112, v113
	v_cvt_pk_bf16_f32 v111, v114, v115
	global_store_dwordx4 v[4:5], v[108:111], off
	v_lshl_add_u64 v[4:5], v[4:5], 0, s[8:9]
	s_waitcnt vmcnt(4)
	v_cvt_pk_bf16_f32 v116, v116, v117
	v_cvt_pk_bf16_f32 v117, v118, v119
	v_cvt_pk_bf16_f32 v118, v120, v121
	v_cvt_pk_bf16_f32 v119, v122, v123
	global_store_dwordx4 v[4:5], v[116:119], off
	v_lshl_add_u64 v[4:5], v[4:5], 0, s[8:9]
	s_waitcnt vmcnt(3)
	v_cvt_pk_bf16_f32 v124, v124, v125
	v_cvt_pk_bf16_f32 v125, v126, v127
	v_cvt_pk_bf16_f32 v126, v128, v129
	v_cvt_pk_bf16_f32 v127, v130, v131
	global_store_dwordx4 v[4:5], v[124:127], off
	v_lshl_add_u64 v[4:5], v[4:5], 0, s[8:9]
	s_branch .Lxc4_head

; __device__ __forceinline__ float ex2(float x) { return __builtin_amdgcn_exp2f(x); }
; __device__ __forceinline__ float halves_max(float x) { auto rr = __builtin_amdgcn_permlane32_swap(__float_as_uint(x), __float_as_uint(x), false, false); return fmaxf(__uint_as_float(rr[0]), __uint_as_float(rr[1])); }
; __device__ __forceinline__ float max3f(float a, float b, float c) { float r; asm("v_max3_f32 %0, %1, %2, %3" : "=v"(r) : "v"(a), "v"(b), "v"(c)); return r; }
;     ...
;                 float mxa = max3f(s0[0], s0[1], s1[0]), mxb = max3f(s0[2], s0[3], s1[1]);
;                 mxa = max3f(mxa, s1[2], s1[3]);
; #pragma unroll
;                 for (int v = 4; v < 16; v += 4) { mxa = max3f(mxa, s0[v], s0[v + 1]); mxb = max3f(mxb, s0[v + 2], s0[v + 3]); mxa = max3f(mxa, s1[v], s1[v + 1]); mxb = max3f(mxb, s1[v + 2], s1[v + 3]); }
;                 const float mx = halves_max(fmaxf(mxa, mxb));
;                 const bool seen = mx > -INFINITY;
;                 const float dlt = fresh ? (seen ? mx : 0.f) : fmaxf(mx, 0.f);
;                 if (__builtin_amdgcn_ballot_w64(dlt != 0.f) != 0ull) {
;                     const float alpha = fresh ? 1.0f : ex2(-dlt);
;                     alpha_t = alpha;
;                     m_run = (fresh ? 0.f : m_run) + dlt;
; #pragma unroll
;                     for (int v = 0; v < 16; ++v) { s0[v] -= dlt; s1[v] -= dlt; }
;                     l_run *= alpha;
; #pragma unroll
;                     for (int d = 0; d < NDV; ++d)
; #pragma unroll
;                         for (int v = 0; v < 16; ++v) o[d][v] *= alpha;
;                 }
.LBB0_360:
	v_max3_f32 v208, v80, v81, v64
	v_max3_f32 v210, v82, v83, v65
	s_nop 0
	v_max3_f32 v208, v208, v66, v67
	v_max3_f32 v210, v210, v86, v87
	s_nop 0
	v_max3_f32 v208, v208, v84, v85
	v_max3_f32 v210, v210, v70, v71
	s_nop 0
	v_max3_f32 v208, v208, v68, v69
	v_max3_f32 v210, v210, v90, v91
	s_nop 0
	v_max3_f32 v208, v208, v88, v89
	v_max3_f32 v210, v210, v74, v75
	s_nop 0
	v_max3_f32 v208, v208, v72, v73
	v_max3_f32 v210, v210, v94, v95
	s_nop 0
	v_max3_f32 v208, v208, v92, v93
	v_max3_f32 v210, v210, v78, v79
	s_nop 0
	v_max3_f32 v208, v208, v76, v77
	v_max_f32_e32 v210, v210, v210
	v_max_f32_e32 v208, v208, v208
	v_max_f32_e32 v208, v208, v210
	v_mov_b32_e32 v210, v208
	s_nop 1
	v_permlane32_swap_b32_e32 v208, v210
	v_max_f32_e32 v210, v210, v210
	v_max_f32_e32 v208, v208, v208
	v_max_f32_e32 v208, v208, v210
	v_cmp_nlg_f32_e64 s[14:15], s70, v208
	s_nop 1
	v_cndmask_b32_e64 v210, v208, 0, s[14:15]
	v_max_f32_e32 v208, 0, v208
	v_cmp_lt_f32_e32 vcc, 4.0, v208
	s_nop 1
	v_cndmask_b32_e32 v208, 0, v208, vcc
	v_cndmask_b32_e64 v210, v208, v210, s[8:9]
	v_cmp_neq_f32_e32 vcc, 0, v210
	s_cbranch_vccz .LBB0_362
	v_exp_f32_e64 v208, -v210
	v_cndmask_b32_e64 v235, v235, 0, s[8:9]
	v_pk_add_f32 v[80:81], v[80:81], v[210:211] op_sel_hi:[1,0] neg_lo:[0,1] neg_hi:[0,1]
	v_pk_add_f32 v[64:65], v[64:65], v[210:211] op_sel_hi:[1,0] neg_lo:[0,1] neg_hi:[0,1]
	v_cndmask_b32_e64 v208, v208, 1.0, s[8:9]
	v_pk_add_f32 v[82:83], v[82:83], v[210:211] op_sel_hi:[1,0] neg_lo:[0,1] neg_hi:[0,1]
	v_pk_add_f32 v[66:67], v[66:67], v[210:211] op_sel_hi:[1,0] neg_lo:[0,1] neg_hi:[0,1]
	v_pk_add_f32 v[84:85], v[84:85], v[210:211] op_sel_hi:[1,0] neg_lo:[0,1] neg_hi:[0,1]
	v_pk_add_f32 v[68:69], v[68:69], v[210:211] op_sel_hi:[1,0] neg_lo:[0,1] neg_hi:[0,1]
	v_pk_add_f32 v[86:87], v[86:87], v[210:211] op_sel_hi:[1,0] neg_lo:[0,1] neg_hi:[0,1]
	v_pk_add_f32 v[70:71], v[70:71], v[210:211] op_sel_hi:[1,0] neg_lo:[0,1] neg_hi:[0,1]
	v_pk_add_f32 v[88:89], v[88:89], v[210:211] op_sel_hi:[1,0] neg_lo:[0,1] neg_hi:[0,1]
	v_pk_add_f32 v[72:73], v[72:73], v[210:211] op_sel_hi:[1,0] neg_lo:[0,1] neg_hi:[0,1]
	v_pk_add_f32 v[90:91], v[90:91], v[210:211] op_sel_hi:[1,0] neg_lo:[0,1] neg_hi:[0,1]
	v_pk_add_f32 v[74:75], v[74:75], v[210:211] op_sel_hi:[1,0] neg_lo:[0,1] neg_hi:[0,1]
	v_pk_add_f32 v[92:93], v[92:93], v[210:211] op_sel_hi:[1,0] neg_lo:[0,1] neg_hi:[0,1]
	v_pk_add_f32 v[76:77], v[76:77], v[210:211] op_sel_hi:[1,0] neg_lo:[0,1] neg_hi:[0,1]
	v_pk_add_f32 v[94:95], v[94:95], v[210:211] op_sel_hi:[1,0] neg_lo:[0,1] neg_hi:[0,1]
	v_pk_add_f32 v[78:79], v[78:79], v[210:211] op_sel_hi:[1,0] neg_lo:[0,1] neg_hi:[0,1]
	v_add_f32_e32 v235, v235, v210
	v_pk_mul_f32 v[62:63], v[62:63], v[208:209] op_sel_hi:[1,0]
	v_pk_mul_f32 v[60:61], v[60:61], v[208:209] op_sel_hi:[1,0]
	v_pk_mul_f32 v[58:59], v[58:59], v[208:209] op_sel_hi:[1,0]
	v_pk_mul_f32 v[56:57], v[56:57], v[208:209] op_sel_hi:[1,0]
	v_pk_mul_f32 v[54:55], v[54:55], v[208:209] op_sel_hi:[1,0]
	v_pk_mul_f32 v[52:53], v[52:53], v[208:209] op_sel_hi:[1,0]
	v_pk_mul_f32 v[50:51], v[50:51], v[208:209] op_sel_hi:[1,0]
	v_pk_mul_f32 v[48:49], v[48:49], v[208:209] op_sel_hi:[1,0]
	v_pk_mul_f32 v[46:47], v[46:47], v[208:209] op_sel_hi:[1,0]
	v_pk_mul_f32 v[44:45], v[44:45], v[208:209] op_sel_hi:[1,0]
	v_pk_mul_f32 v[42:43], v[42:43], v[208:209] op_sel_hi:[1,0]
	v_pk_mul_f32 v[40:41], v[40:41], v[208:209] op_sel_hi:[1,0]
	v_pk_mul_f32 v[38:39], v[38:39], v[208:209] op_sel_hi:[1,0]
	v_pk_mul_f32 v[36:37], v[36:37], v[208:209] op_sel_hi:[1,0]
	v_pk_mul_f32 v[34:35], v[34:35], v[208:209] op_sel_hi:[1,0]
	v_pk_mul_f32 v[32:33], v[32:33], v[208:209] op_sel_hi:[1,0]
	v_pk_mul_f32 v[30:31], v[30:31], v[208:209] op_sel_hi:[1,0]
	v_pk_mul_f32 v[28:29], v[28:29], v[208:209] op_sel_hi:[1,0]
	v_pk_mul_f32 v[26:27], v[26:27], v[208:209] op_sel_hi:[1,0]
	v_pk_mul_f32 v[24:25], v[24:25], v[208:209] op_sel_hi:[1,0]
	v_pk_mul_f32 v[22:23], v[22:23], v[208:209] op_sel_hi:[1,0]
	v_pk_mul_f32 v[20:21], v[20:21], v[208:209] op_sel_hi:[1,0]
	v_pk_mul_f32 v[18:19], v[18:19], v[208:209] op_sel_hi:[1,0]
	v_pk_mul_f32 v[16:17], v[16:17], v[208:209] op_sel_hi:[1,0]
	v_pk_mul_f32 v[14:15], v[14:15], v[208:209] op_sel_hi:[1,0]
	v_pk_mul_f32 v[12:13], v[12:13], v[208:209] op_sel_hi:[1,0]
	v_pk_mul_f32 v[10:11], v[10:11], v[208:209] op_sel_hi:[1,0]
	v_pk_mul_f32 v[8:9], v[8:9], v[208:209] op_sel_hi:[1,0]
	v_pk_mul_f32 v[6:7], v[6:7], v[208:209] op_sel_hi:[1,0]
	v_pk_mul_f32 v[4:5], v[4:5], v[208:209] op_sel_hi:[1,0]
	v_pk_mul_f32 v[2:3], v[2:3], v[208:209] op_sel_hi:[1,0]
	v_pk_mul_f32 v[0:1], v[0:1], v[208:209] op_sel_hi:[1,0]
	v_mul_f32_e32 v233, v233, v208
	s_branch .LBB0_363

; __device__ __forceinline__ unsigned cvt_pk_bf16(float lo, float hi) { unsigned r; asm volatile("v_cvt_pk_bf16_f32 %0, %1, %2" : "=v"(r) : "v"(lo), "v"(hi)); return r; }
; #define LAS __attribute__((address_space(3)))
; __device__ __forceinline__ float halves_sum(float x) { auto rr = __builtin_amdgcn_permlane32_swap(__float_as_uint(x), __float_as_uint(x), false, false); return __uint_as_float(rr[0]) + __uint_as_float(rr[1]); }
;     ...
;     __builtin_amdgcn_s_setprio(0);
;     __syncthreads();
;     if (MODE == 0) {
;         float inv = 1.0f / halves_sum(l_run);
;         if (SHARE) {
;             if (primary) *(LAS float*)(pslot + 68) = inv;
;             __syncthreads();
;             if (!primary) inv = *(const LAS float*)(pslot + 68);
;         }
; #pragma unroll
;         for (int d = 0; d < NDV; ++d)
; #pragma unroll
;             for (int v = 0; v < 16; ++v) o[d][v] *= inv;
;     }
; template <int NDV>
; __device__ __forceinline__ void store_o(const f32x16 (&o)[NDV], bf16_t* dst  , int half) {
; #pragma unroll
;     for (int d = 0; d < NDV; ++d)
; #pragma unroll
;         for (int i = 0; i < 4; ++i) {
;             u32x2 w; w.x = cvt_pk_bf16(o[d][4 * i], o[d][4 * i + 1]); w.y = cvt_pk_bf16(o[d][4 * i + 2], o[d][4 * i + 3]);
;             *(u32x2*)(dst + 32 * d + 8 * i + 4 * half) = w;
;         }
; }
.LBB0_1119:
	s_setprio 0
	v_mov_b32_e32 v64, v197
	s_nop 1
	v_permlane32_swap_b32_e32 v197, v64
	v_add_f32_e32 v64, v197, v64
	v_div_scale_f32 v65, s[20:21], v64, v64, 1.0
	v_rcp_f32_e32 v66, v65
	s_lshl_b32 s20, s56, 12
	s_or_b32 s20, s20, s75
	s_mov_b32 s59, s45
	v_fma_f32 v67, -v65, v66, 1.0
	v_fmac_f32_e32 v66, v67, v66
	v_div_scale_f32 v67, vcc, 1.0, v64, 1.0
	v_mul_f32_e32 v68, v67, v66
	v_fma_f32 v69, -v65, v68, v67
	v_fmac_f32_e32 v68, v69, v66
	v_fma_f32 v65, -v65, v68, v67
	v_div_fmas_f32 v65, v65, v66, v68
	v_div_fixup_f32 v64, v65, v64, 1.0
	v_mul_f32_e32 v65, v0, v64
	v_add_u32_e32 v0, s20, v227
	v_mul_f32_e32 v66, v1, v64
	v_ashrrev_i32_e32 v1, 31, v0
	v_lshlrev_b64 v[0:1], 12, v[0:1]
	v_lshl_add_u64 v[0:1], s[46:47], 0, v[0:1]
	v_mul_f32_e32 v67, v2, v64
	v_mul_f32_e32 v68, v3, v64
	v_lshl_add_u64 v[0:1], v[0:1], 0, s[58:59]
	v_lshlrev_b32_e32 v2, 1, v182
	v_mov_b32_e32 v3, v165
	s_barrier
	v_mul_f32_e32 v48, v48, v64
	v_mul_f32_e32 v49, v49, v64
	v_mul_f32_e32 v50, v50, v64
	v_mul_f32_e32 v51, v51, v64
	v_lshl_add_u64 v[0:1], v[0:1], 0, v[2:3]
	v_cvt_pk_bf16_f32 v2, v48, v49
	v_cvt_pk_bf16_f32 v3, v50, v51
	v_mul_f32_e32 v52, v52, v64
	v_mul_f32_e32 v53, v53, v64
	v_mul_f32_e32 v54, v54, v64
	v_mul_f32_e32 v55, v55, v64
	global_store_dwordx2 v[0:1], v[2:3], off
	v_cvt_pk_bf16_f32 v2, v52, v53
	v_cvt_pk_bf16_f32 v3, v54, v55
	v_mul_f32_e32 v56, v56, v64
	v_mul_f32_e32 v57, v57, v64
	v_mul_f32_e32 v58, v58, v64
	v_mul_f32_e32 v59, v59, v64
	global_store_dwordx2 v[0:1], v[2:3], off offset:16
	v_cvt_pk_bf16_f32 v2, v56, v57
	v_cvt_pk_bf16_f32 v3, v58, v59
	v_mul_f32_e32 v60, v60, v64
	v_mul_f32_e32 v61, v61, v64
	v_mul_f32_e32 v62, v62, v64
	v_mul_f32_e32 v63, v63, v64
	global_store_dwordx2 v[0:1], v[2:3], off offset:32
	v_cvt_pk_bf16_f32 v2, v60, v61
	v_cvt_pk_bf16_f32 v3, v62, v63
	v_mul_f32_e32 v32, v32, v64
	v_mul_f32_e32 v33, v33, v64
	v_mul_f32_e32 v34, v34, v64
	v_mul_f32_e32 v35, v35, v64
	global_store_dwordx2 v[0:1], v[2:3], off offset:48
	v_cvt_pk_bf16_f32 v2, v32, v33
	v_cvt_pk_bf16_f32 v3, v34, v35
	v_mul_f32_e32 v36, v36, v64
	v_mul_f32_e32 v37, v37, v64
	v_mul_f32_e32 v38, v38, v64
	v_mul_f32_e32 v39, v39, v64
	global_store_dwordx2 v[0:1], v[2:3], off offset:64
	v_cvt_pk_bf16_f32 v2, v36, v37
	v_cvt_pk_bf16_f32 v3, v38, v39
	v_mul_f32_e32 v40, v40, v64
	v_mul_f32_e32 v41, v41, v64
	v_mul_f32_e32 v42, v42, v64
	v_mul_f32_e32 v43, v43, v64
	global_store_dwordx2 v[0:1], v[2:3], off offset:80
	v_cvt_pk_bf16_f32 v2, v40, v41
	v_cvt_pk_bf16_f32 v3, v42, v43
	v_mul_f32_e32 v44, v44, v64
	v_mul_f32_e32 v45, v45, v64
	v_mul_f32_e32 v46, v46, v64
	v_mul_f32_e32 v47, v47, v64
	global_store_dwordx2 v[0:1], v[2:3], off offset:96
	v_cvt_pk_bf16_f32 v2, v44, v45
	v_cvt_pk_bf16_f32 v3, v46, v47
	v_mul_f32_e32 v16, v16, v64
	v_mul_f32_e32 v17, v17, v64
	v_mul_f32_e32 v18, v18, v64
	v_mul_f32_e32 v19, v19, v64
	global_store_dwordx2 v[0:1], v[2:3], off offset:112
	v_cvt_pk_bf16_f32 v2, v16, v17
	v_cvt_pk_bf16_f32 v3, v18, v19
	v_mul_f32_e32 v20, v20, v64
	v_mul_f32_e32 v21, v21, v64
	v_mul_f32_e32 v22, v22, v64
	v_mul_f32_e32 v23, v23, v64
	global_store_dwordx2 v[0:1], v[2:3], off offset:128
	v_cvt_pk_bf16_f32 v2, v20, v21
	v_cvt_pk_bf16_f32 v3, v22, v23
	v_mul_f32_e32 v24, v24, v64
	v_mul_f32_e32 v25, v25, v64
	v_mul_f32_e32 v26, v26, v64
	v_mul_f32_e32 v27, v27, v64
	global_store_dwordx2 v[0:1], v[2:3], off offset:144
	v_cvt_pk_bf16_f32 v2, v24, v25
	v_cvt_pk_bf16_f32 v3, v26, v27
	v_mul_f32_e32 v28, v28, v64
	v_mul_f32_e32 v29, v29, v64
	v_mul_f32_e32 v30, v30, v64
	v_mul_f32_e32 v31, v31, v64
	global_store_dwordx2 v[0:1], v[2:3], off offset:160
	v_cvt_pk_bf16_f32 v2, v28, v29
	v_cvt_pk_bf16_f32 v3, v30, v31
	global_store_dwordx2 v[0:1], v[2:3], off offset:176
	v_cvt_pk_bf16_f32 v2, v65, v66
	v_cvt_pk_bf16_f32 v3, v67, v68
	v_mul_f32_e32 v4, v4, v64
	v_mul_f32_e32 v5, v5, v64
	v_mul_f32_e32 v6, v6, v64
	v_mul_f32_e32 v7, v7, v64
	global_store_dwordx2 v[0:1], v[2:3], off offset:192
	v_cvt_pk_bf16_f32 v2, v4, v5
	v_cvt_pk_bf16_f32 v3, v6, v7
	v_mul_f32_e32 v8, v8, v64
	v_mul_f32_e32 v9, v9, v64
	v_mul_f32_e32 v10, v10, v64
	v_mul_f32_e32 v11, v11, v64
	global_store_dwordx2 v[0:1], v[2:3], off offset:208
	v_cvt_pk_bf16_f32 v2, v8, v9
	v_cvt_pk_bf16_f32 v3, v10, v11
	s_mov_b64 s[20:21], 0
	v_mul_f32_e32 v12, v12, v64
	v_mul_f32_e32 v13, v13, v64
	v_mul_f32_e32 v14, v14, v64
	v_mul_f32_e32 v15, v15, v64
	global_store_dwordx2 v[0:1], v[2:3], off offset:224
	v_cvt_pk_bf16_f32 v2, v12, v13
	v_cvt_pk_bf16_f32 v3, v14, v15
	global_store_dwordx2 v[0:1], v[2:3], off offset:240

; #define LAS __attribute__((address_space(3)))
; #define ATT_LOADK(k0_) do { _Pragma("unroll") for (int i_ = 0; i_ < NKCH; ++i_) { const int id_ = tid + 512 * i_, row_ = id_ / KCH, cc_ = id_ % KCH; \
;         const bf16_t* src_ = (DQK == 128 || cc_ < 16) ? K1 + (size_t)((k0_) + row_) * ldk1 + cc_ * 8 : K2 + (size_t)((k0_) + row_) * ldk2 + (cc_ - 16) * 8; \
;         kst[i_] = *(const u32x4*)src_; } } while (0)
; #define ATT_LOADV(k0_) do { _Pragma("unroll") for (int i_ = 0; i_ < NVCH; ++i_) { const int id_ = tid + 512 * i_, dv_ = id_ >> 3, cc_ = id_ & 7; \
;         vst[i_] = *(const u32x4*)(Vt + (size_t)dv_ * SEQ + (k0_) + cc_ * 8); } } while (0)
; #define ATT_STOREK(buf_) do { _Pragma("unroll") for (int i_ = 0; i_ < NKCH; ++i_) { const int id_ = tid + 512 * i_, row_ = id_ / KCH, cc_ = id_ % KCH; \
;         *(LAS u32x4*)(lds + (buf_) * KBUF + row_ * KROW + cc_ * 16) = kst[i_]; } } while (0)
; #define ATT_STOREV(buf_) do { _Pragma("unroll") for (int i_ = 0; i_ < NVCH; ++i_) { const int id_ = tid + 512 * i_, dv_ = id_ >> 3, cc_ = id_ & 7; \
;         LAS unsigned char* d_ = lds + OFF_V + (buf_) * VBUF + dv_ * VROW + cc_ * 16; \
;         *(LAS u32x2*)d_ = (u32x2){vst[i_].x, vst[i_].y}; *(LAS u32x2*)(d_ + 8) = (u32x2){vst[i_].z, vst[i_].w}; } } while (0)
; #define ATT_LOADK(k0_) do { _Pragma("unroll") for (int i_ = 0; i_ < NKCH; ++i_) { const int id_ = tid + 512 * i_, row_ = id_ / KCH, cc_ = id_ % KCH; \
;         const bf16_t* src_ = (DQK == 128 || cc_ < 16) ? K1 + (size_t)((k0_) + row_) * ldk1 + cc_ * 8 : K2 + (size_t)((k0_) + row_) * ldk2 + (cc_ - 16) * 8; \
;         kst[i_] = *(const u32x4*)src_; } } while (0)
;     ...
;     for (int d = 0; d < NDV; ++d)
; #pragma unroll
;         for (int v = 0; v < 16; ++v) o[d][v] = 0.f;
;     float m_run = 0.f, l_run = 0.f, carry = 0.f;
;     bool wave_done = false, fresh = true;
;     LAS volatile unsigned* flag = (LAS volatile unsigned*)(lds + OFF_FLAG);
;     const int ntiles = (q0 + QROWS) >> 6;
;     const int wave_first_row = q0 + wq * 32, wave_last_row = wave_first_row + 31;
;     u32x4 kst[NKCH], vst[NVCH];
;     ...
;     int kt = ntiles - 1;
;     ATT_LOADK(kt * 64); ATT_LOADV(kt * 64); ATT_STOREK(0); ATT_STOREV(0);
.LBB0_1140:
	v_add_u32_e32 v2, s75, v228
	v_ashrrev_i32_e32 v3, 31, v2
	v_lshl_add_u64 v[0:1], v[184:185], 0, s[22:23]
	v_lshlrev_b64 v[4:5], 7, v[2:3]
	v_lshl_add_u64 v[198:199], v[0:1], 0, v[4:5]
	v_lshl_add_u64 v[0:1], v[186:187], 0, s[20:21]
	v_lshlrev_b64 v[2:3], 12, v[2:3]
	s_lshl_b32 s24, s78, 7
	v_lshl_add_u64 v[0:1], v[0:1], 0, v[2:3]
	v_add_u32_e32 v2, s75, v229
	s_lshl_b32 s58, s24, 1
	s_mov_b32 s59, s45
	v_ashrrev_i32_e32 v3, 31, v2
	v_lshl_add_u64 v[200:201], v[0:1], 0, s[58:59]
	v_lshl_add_u64 v[0:1], v[188:189], 0, s[22:23]
	v_lshlrev_b64 v[4:5], 7, v[2:3]
	v_lshl_add_u64 v[202:203], v[0:1], 0, v[4:5]
	v_lshl_add_u64 v[0:1], v[190:191], 0, s[20:21]
	v_lshlrev_b64 v[2:3], 12, v[2:3]
	v_lshl_add_u64 v[0:1], v[0:1], 0, v[2:3]
	v_add_u32_e32 v2, s75, v230
	v_ashrrev_i32_e32 v3, 31, v2
	v_lshl_add_u64 v[204:205], v[0:1], 0, s[58:59]
	v_lshl_add_u64 v[0:1], v[192:193], 0, s[22:23]
	v_lshlrev_b64 v[4:5], 7, v[2:3]
	v_lshl_add_u64 v[206:207], v[0:1], 0, v[4:5]
	v_lshl_add_u64 v[0:1], v[194:195], 0, s[20:21]
	v_lshlrev_b64 v[2:3], 12, v[2:3]
	v_lshl_add_u64 v[0:1], v[0:1], 0, v[2:3]
	v_mov_b32_e32 v14, v165
	v_mov_b32_e32 v15, v165
	v_lshl_add_u64 v[208:209], v[0:1], 0, s[58:59]
	v_mov_b32_e32 v0, v165
	v_mov_b32_e32 v1, v165
	v_mov_b32_e32 v2, v165
	v_mov_b32_e32 v3, v165
	v_mov_b32_e32 v4, v165
	v_mov_b32_e32 v5, v165
	v_mov_b32_e32 v6, v165
	v_mov_b32_e32 v7, v165
	v_mov_b32_e32 v8, v165
	v_mov_b32_e32 v9, v165
	v_mov_b32_e32 v10, v165
	v_mov_b32_e32 v11, v165
	v_mov_b32_e32 v12, v165
	v_mov_b32_e32 v13, v165
	v_mov_b32_e32 v64, 0
	v_mov_b64_e32 v[30:31], v[14:15]
	v_mov_b64_e32 v[46:47], v[14:15]
	v_mov_b64_e32 v[62:63], v[14:15]
	s_or_b32 s78, s57, 31
	s_add_i32 s79, s75, 0xff
	s_mov_b32 s59, 0
	v_mov_b32_e32 v197, 0
	s_mov_b64 s[20:21], -1
	v_mov_b32_e32 v239, s44
	v_mov_b64_e32 v[28:29], v[12:13]
	v_mov_b64_e32 v[26:27], v[10:11]
	v_mov_b64_e32 v[24:25], v[8:9]
	v_mov_b64_e32 v[22:23], v[6:7]
	v_mov_b64_e32 v[20:21], v[4:5]
	v_mov_b64_e32 v[18:19], v[2:3]
	v_mov_b64_e32 v[16:17], v[0:1]
	v_mov_b64_e32 v[44:45], v[12:13]
	v_mov_b64_e32 v[42:43], v[10:11]
	v_mov_b64_e32 v[40:41], v[8:9]
	v_mov_b64_e32 v[38:39], v[6:7]
	v_mov_b64_e32 v[36:37], v[4:5]
	v_mov_b64_e32 v[34:35], v[2:3]
	v_mov_b64_e32 v[32:33], v[0:1]
	v_mov_b64_e32 v[60:61], v[12:13]
	v_mov_b64_e32 v[58:59], v[10:11]
	v_mov_b64_e32 v[56:57], v[8:9]
	v_mov_b64_e32 v[54:55], v[6:7]
	v_mov_b64_e32 v[52:53], v[4:5]
	v_mov_b64_e32 v[50:51], v[2:3]
	v_mov_b64_e32 v[48:49], v[0:1]
	v_mov_b32_e32 v240, 0
	v_mov_b32_e32 v65, v64
	v_mov_b32_e32 v66, v64
	v_mov_b32_e32 v67, v64
	v_mov_b32_e32 v72, v64
	v_mov_b32_e32 v73, v64
	v_mov_b32_e32 v74, v64
	v_mov_b32_e32 v75, v64
	v_mov_b32_e32 v68, v64
	v_mov_b32_e32 v69, v64
	v_mov_b32_e32 v70, v64
	v_mov_b32_e32 v71, v64
	v_mov_b32_e32 v76, v64
	v_mov_b32_e32 v77, v64
	v_mov_b32_e32 v78, v64
	v_mov_b32_e32 v79, v64
	s_branch .LBB0_1142
.LBB0_1141:
	s_add_i32 s59, s59, 1
	s_sub_i32 s79, s79, 64
	v_lshl_add_u64 v[198:199], v[198:199], 0, s[52:53]
	v_lshl_add_u64 v[200:201], v[200:201], 0, s[54:55]
	v_lshl_add_u64 v[202:203], v[202:203], 0, s[52:53]
	v_lshl_add_u64 v[204:205], v[204:205], 0, s[54:55]
	v_lshl_add_u64 v[206:207], v[206:207], 0, s[52:53]
	v_lshl_add_u64 v[208:209], v[208:209], 0, s[54:55]
	s_cbranch_execz .LBB0_1119

; #define ATT_LOADK(k0_) do { _Pragma("unroll") for (int i_ = 0; i_ < NKCH; ++i_) { const int id_ = tid + 512 * i_, row_ = id_ / KCH, cc_ = id_ % KCH; \
;         const bf16_t* src_ = (DQK == 128 || cc_ < 16) ? K1 + (size_t)((k0_) + row_) * ldk1 + cc_ * 8 : K2 + (size_t)((k0_) + row_) * ldk2 + (cc_ - 16) * 8; \
;         kst[i_] = *(const u32x4*)src_; } } while (0)
; #define ATT_LOADV(k0_) do { _Pragma("unroll") for (int i_ = 0; i_ < NVCH; ++i_) { const int id_ = tid + 512 * i_, dv_ = id_ >> 3, cc_ = id_ & 7; \
;         vst[i_] = *(const u32x4*)(Vt + (size_t)dv_ * SEQ + (k0_) + cc_ * 8); } } while (0)
; #define ATT_LOADK(k0_) do { _Pragma("unroll") for (int i_ = 0; i_ < NKCH; ++i_) { const int id_ = tid + 512 * i_, row_ = id_ / KCH, cc_ = id_ % KCH; \
;         const bf16_t* src_ = (DQK == 128 || cc_ < 16) ? K1 + (size_t)((k0_) + row_) * ldk1 + cc_ * 8 : K2 + (size_t)((k0_) + row_) * ldk2 + (cc_ - 16) * 8; \
;         kst[i_] = *(const u32x4*)src_; } } while (0)
; #define ATT_LOADV(k0_, part_) do { _Pragma("unroll") for (int i_ = 0; i_ < NVS; ++i_) { const int id_ = tid + 512 * (i_ + (part_) * NVS), dv_ = id_ >> 3, cc_ = id_ & 7; \
;         vst[i_] = *(const u32x4*)(Vt + (size_t)dv_ * SEQ + (k0_) + cc_ * 8); } } while (0)
;     ...
;         const int buf = it & 1, k0 = kt * 64;
;         if (MODE == 1 && it > 0) {
;             unsigned all = 1u;
; #pragma unroll
;             for (int w = 0; w < 8; ++w) all &= flag[((it - 1) & 1) * 8 + w];
;             if (all) break;
;         }
;         const bool has_next = kt > 0;
;         if (has_next) { ATT_LOADK(k0 - 64); ATT_LOADV(k0 - 64); }
;         const bool active = (k0 <= wave_last_row) && !wave_done;
.LBB0_1144:
	s_and_b32 s80, s59, 1
	s_cmp_le_i32 s44, s78
	s_cselect_b64 s[60:61], -1, 0
	s_cmp_gt_i32 s44, s78
	s_cbranch_scc0 .LBB0_1150
	s_andn2_b64 vcc, exec, s[60:61]
	s_cbranch_vccz .LBB0_1155

; #define ATT_STOREK(buf_) do { _Pragma("unroll") for (int i_ = 0; i_ < NKCH; ++i_) { const int id_ = tid + 512 * i_, row_ = id_ / KCH, cc_ = id_ % KCH; \
;         *(LAS u32x4*)(lds + (buf_) * KBUF + row_ * KROW + cc_ * 16) = kst[i_]; } } while (0)
; #define ATT_STOREV(buf_) do { _Pragma("unroll") for (int i_ = 0; i_ < NVCH; ++i_) { const int id_ = tid + 512 * i_, dv_ = id_ >> 3, cc_ = id_ & 7; \
;         LAS unsigned char* d_ = lds + OFF_V + (buf_) * VBUF + dv_ * VROW + cc_ * 16; \
;         *(LAS u32x2*)d_ = (u32x2){vst[i_].x, vst[i_].y}; *(LAS u32x2*)(d_ + 8) = (u32x2){vst[i_].z, vst[i_].w}; } } while (0)
; #define ATT_STOREK(kofs_) do { _Pragma("unroll") for (int i_ = 0; i_ < NKCH; ++i_) { const int id_ = tid + 512 * i_, row_ = id_ / KCH, cc_ = id_ % KCH; \
;         *(LAS u32x4*)(lds + (kofs_) + row_ * KROW + cc_ * 16) = kst[i_]; } } while (0)
; #define ATT_STOREV(buf_, part_) do { _Pragma("unroll") for (int i_ = 0; i_ < NVS; ++i_) { const int id_ = tid + 512 * (i_ + (part_) * NVS), dv_ = id_ >> 3, cc_ = id_ & 7; \
;         LAS unsigned char* d_ = lds + OFF_V + (buf_) * VBUF + dv_ * VROW + cc_ * 16; \
;         *(LAS u32x2*)d_ = (u32x2){vst[i_].x, vst[i_].y}; *(LAS u32x2*)(d_ + 8) = (u32x2){vst[i_].z, vst[i_].w}; } } while (0)
;     ...
;         if (has_next) { ATT_STOREK(buf ^ 1); ATT_STOREV(buf ^ 1); }
.LBB0_1147:
	s_xor_b32 s22, s80, 1
	s_mul_i32 s23, s22, 0x6400
	v_add3_u32 v80, s23, v216, v217
	s_waitcnt vmcnt(4)
	ds_write_b128 v80, v[144:147]
	v_add3_u32 v80, s23, v218, v219
	s_waitcnt vmcnt(3)
	ds_write_b128 v80, v[148:151]
	v_add3_u32 v80, s23, v220, v221
	s_mulk_i32 s22, 0x4400
	s_waitcnt vmcnt(2)
	ds_write_b128 v80, v[152:155]
	v_or_b32_e32 v80, s22, v222
	v_add3_u32 v81, v80, v223, s73
	v_add3_u32 v80, v80, v224, s73
	s_waitcnt vmcnt(1)
	ds_write2_b64 v81, v[156:157], v[158:159] offset1:1
	s_waitcnt vmcnt(0)
	ds_write2_b64 v80, v[160:161], v[162:163] offset1:1

; __device__ __forceinline__ float ex2(float x) { return __builtin_amdgcn_exp2f(x); }
; __device__ __forceinline__ float halves_max(float x) { auto rr = __builtin_amdgcn_permlane32_swap(__float_as_uint(x), __float_as_uint(x), false, false); return fmaxf(__uint_as_float(rr[0]), __uint_as_float(rr[1])); }
; __device__ __forceinline__ float max3f(float a, float b, float c) { float r; asm("v_max3_f32 %0, %1, %2, %3" : "=v"(r) : "v"(a), "v"(b), "v"(c)); return r; }
;     ...
;                 float mxa = max3f(s0[0], s0[1], s1[0]), mxb = max3f(s0[2], s0[3], s1[1]);
;                 mxa = max3f(mxa, s1[2], s1[3]);
; #pragma unroll
;                 for (int v = 4; v < 16; v += 4) { mxa = max3f(mxa, s0[v], s0[v + 1]); mxb = max3f(mxb, s0[v + 2], s0[v + 3]); mxa = max3f(mxa, s1[v], s1[v + 1]); mxb = max3f(mxb, s1[v + 2], s1[v + 3]); }
;                 const float mx = halves_max(fmaxf(mxa, mxb));
;                 const bool seen = mx > -INFINITY;
;                 const float dlt = fresh ? (seen ? mx : 0.f) : fmaxf(mx, 0.f);
;                 if (__builtin_amdgcn_ballot_w64(dlt != 0.f) != 0ull) {
;                     const float alpha = fresh ? 1.0f : ex2(-dlt);
;                     alpha_t = alpha;
;                     m_run = (fresh ? 0.f : m_run) + dlt;
; #pragma unroll
;                     for (int v = 0; v < 16; ++v) { s0[v] -= dlt; s1[v] -= dlt; }
;                     l_run *= alpha;
; #pragma unroll
;                     for (int d = 0; d < NDV; ++d)
; #pragma unroll
;                         for (int v = 0; v < 16; ++v) o[d][v] *= alpha;
;                 }
.LBB0_1152:
	v_max3_f32 v210, v80, v81, v64
	v_max3_f32 v211, v82, v83, v65
	s_nop 0
	v_max3_f32 v210, v210, v66, v67
	v_max3_f32 v211, v211, v86, v87
	s_nop 0
	v_max3_f32 v210, v210, v84, v85
	v_max3_f32 v211, v211, v70, v71
	s_nop 0
	v_max3_f32 v210, v210, v68, v69
	v_max3_f32 v211, v211, v90, v91
	s_nop 0
	v_max3_f32 v210, v210, v88, v89
	v_max3_f32 v211, v211, v74, v75
	s_nop 0
	v_max3_f32 v210, v210, v72, v73
	v_max3_f32 v211, v211, v94, v95
	s_nop 0
	v_max3_f32 v210, v210, v92, v93
	v_max3_f32 v211, v211, v78, v79
	s_nop 0
	v_max3_f32 v210, v210, v76, v77
	v_max_f32_e32 v211, v211, v211
	v_max_f32_e32 v210, v210, v210
	v_max_f32_e32 v210, v210, v211
	v_mov_b32_e32 v211, v210
	s_nop 1
	v_permlane32_swap_b32_e32 v210, v211
	v_max_f32_e32 v211, v211, v211
	v_max_f32_e32 v210, v210, v210
	v_max_f32_e32 v210, v210, v211
	v_cmp_nlg_f32_e64 s[24:25], s74, v210
	s_nop 1
	v_cndmask_b32_e64 v211, v210, 0, s[24:25]
	v_max_f32_e32 v210, 0, v210
	v_cmp_lt_f32_e32 vcc, 4.0, v210
	s_nop 1
	v_cndmask_b32_e32 v210, 0, v210, vcc
	v_cndmask_b32_e64 v210, v210, v211, s[20:21]
	v_cmp_neq_f32_e32 vcc, 0, v210
	s_cbranch_vccz .LBB0_1154
	v_exp_f32_e64 v211, -v210
	s_nop 0
	v_pk_add_f32 v[80:81], v[80:81], v[210:211] op_sel_hi:[1,0] neg_lo:[0,1] neg_hi:[0,1]
	v_pk_add_f32 v[64:65], v[64:65], v[210:211] op_sel_hi:[1,0] neg_lo:[0,1] neg_hi:[0,1]
	v_pk_add_f32 v[82:83], v[82:83], v[210:211] op_sel_hi:[1,0] neg_lo:[0,1] neg_hi:[0,1]
	v_cndmask_b32_e64 v242, v211, 1.0, s[20:21]
	v_pk_add_f32 v[66:67], v[66:67], v[210:211] op_sel_hi:[1,0] neg_lo:[0,1] neg_hi:[0,1]
	v_pk_add_f32 v[84:85], v[84:85], v[210:211] op_sel_hi:[1,0] neg_lo:[0,1] neg_hi:[0,1]
	v_pk_add_f32 v[68:69], v[68:69], v[210:211] op_sel_hi:[1,0] neg_lo:[0,1] neg_hi:[0,1]
	v_pk_add_f32 v[86:87], v[86:87], v[210:211] op_sel_hi:[1,0] neg_lo:[0,1] neg_hi:[0,1]
	v_pk_add_f32 v[70:71], v[70:71], v[210:211] op_sel_hi:[1,0] neg_lo:[0,1] neg_hi:[0,1]
	v_pk_add_f32 v[88:89], v[88:89], v[210:211] op_sel_hi:[1,0] neg_lo:[0,1] neg_hi:[0,1]
	v_pk_add_f32 v[72:73], v[72:73], v[210:211] op_sel_hi:[1,0] neg_lo:[0,1] neg_hi:[0,1]
	v_pk_add_f32 v[90:91], v[90:91], v[210:211] op_sel_hi:[1,0] neg_lo:[0,1] neg_hi:[0,1]
	v_pk_add_f32 v[74:75], v[74:75], v[210:211] op_sel_hi:[1,0] neg_lo:[0,1] neg_hi:[0,1]
	v_pk_add_f32 v[92:93], v[92:93], v[210:211] op_sel_hi:[1,0] neg_lo:[0,1] neg_hi:[0,1]
	v_pk_add_f32 v[76:77], v[76:77], v[210:211] op_sel_hi:[1,0] neg_lo:[0,1] neg_hi:[0,1]
	v_pk_add_f32 v[94:95], v[94:95], v[210:211] op_sel_hi:[1,0] neg_lo:[0,1] neg_hi:[0,1]
	v_pk_add_f32 v[78:79], v[78:79], v[210:211] op_sel_hi:[1,0] neg_lo:[0,1] neg_hi:[0,1]
	v_cndmask_b32_e64 v211, v240, 0, s[20:21]
	v_add_f32_e32 v240, v211, v210
	v_pk_mul_f32 v[62:63], v[62:63], v[242:243] op_sel_hi:[1,0]
	v_pk_mul_f32 v[60:61], v[60:61], v[242:243] op_sel_hi:[1,0]
	v_pk_mul_f32 v[58:59], v[58:59], v[242:243] op_sel_hi:[1,0]
	v_pk_mul_f32 v[56:57], v[56:57], v[242:243] op_sel_hi:[1,0]
	v_pk_mul_f32 v[54:55], v[54:55], v[242:243] op_sel_hi:[1,0]
	v_pk_mul_f32 v[52:53], v[52:53], v[242:243] op_sel_hi:[1,0]
	v_pk_mul_f32 v[50:51], v[50:51], v[242:243] op_sel_hi:[1,0]
	v_pk_mul_f32 v[48:49], v[48:49], v[242:243] op_sel_hi:[1,0]
	v_pk_mul_f32 v[46:47], v[46:47], v[242:243] op_sel_hi:[1,0]
	v_pk_mul_f32 v[44:45], v[44:45], v[242:243] op_sel_hi:[1,0]
	v_pk_mul_f32 v[42:43], v[42:43], v[242:243] op_sel_hi:[1,0]
	v_pk_mul_f32 v[40:41], v[40:41], v[242:243] op_sel_hi:[1,0]
	v_pk_mul_f32 v[38:39], v[38:39], v[242:243] op_sel_hi:[1,0]
	v_pk_mul_f32 v[36:37], v[36:37], v[242:243] op_sel_hi:[1,0]
	v_pk_mul_f32 v[34:35], v[34:35], v[242:243] op_sel_hi:[1,0]
	v_pk_mul_f32 v[32:33], v[32:33], v[242:243] op_sel_hi:[1,0]
	v_pk_mul_f32 v[30:31], v[30:31], v[242:243] op_sel_hi:[1,0]
	v_pk_mul_f32 v[28:29], v[28:29], v[242:243] op_sel_hi:[1,0]
	v_pk_mul_f32 v[26:27], v[26:27], v[242:243] op_sel_hi:[1,0]
	v_pk_mul_f32 v[24:25], v[24:25], v[242:243] op_sel_hi:[1,0]
	v_pk_mul_f32 v[22:23], v[22:23], v[242:243] op_sel_hi:[1,0]
	v_pk_mul_f32 v[20:21], v[20:21], v[242:243] op_sel_hi:[1,0]
	v_pk_mul_f32 v[18:19], v[18:19], v[242:243] op_sel_hi:[1,0]
	v_pk_mul_f32 v[16:17], v[16:17], v[242:243] op_sel_hi:[1,0]
	v_pk_mul_f32 v[14:15], v[14:15], v[242:243] op_sel_hi:[1,0]
	v_pk_mul_f32 v[12:13], v[12:13], v[242:243] op_sel_hi:[1,0]
	v_pk_mul_f32 v[10:11], v[10:11], v[242:243] op_sel_hi:[1,0]
	v_pk_mul_f32 v[8:9], v[8:9], v[242:243] op_sel_hi:[1,0]
	v_pk_mul_f32 v[6:7], v[6:7], v[242:243] op_sel_hi:[1,0]
	v_pk_mul_f32 v[4:5], v[4:5], v[242:243] op_sel_hi:[1,0]
	v_pk_mul_f32 v[2:3], v[2:3], v[242:243] op_sel_hi:[1,0]
	v_pk_mul_f32 v[0:1], v[0:1], v[242:243] op_sel_hi:[1,0]
	v_mul_f32_e32 v197, v197, v242

; #define LAS __attribute__((address_space(3)))
; #define ATT_LOADVG(dst_, kb2_, ip_) do { _Pragma("unroll") for (int d_ = 0; d_ < NDV; ++d_) { \
;                 const u32x2 lo_ = *(const LAS u32x2*)(vb + d_ * 32 * VROW + (kb2_) * 64 + (ip_) * 32), hi_ = *(const LAS u32x2*)(vb + d_ * 32 * VROW + (kb2_) * 64 + (ip_) * 32 + 16); \
;                 dst_[d_] = (u32x4){lo_.x, lo_.y, hi_.x, hi_.y}; } } while (0)
; #define ATT_PVMMA(src_, kb2_, ip_) do { _Pragma("unroll") for (int d_ = 0; d_ < NDV; ++d_) o[d_] = __builtin_amdgcn_mfma_f32_32x32x16_bf16(__builtin_bit_cast(bf16x8, src_[d_]), pb[kb2_][ip_], o[d_], 0, 0, 0); } while (0)
;     ...
;             if (MODE == 0 && DQK != 128) {
; #pragma unroll
;                 for (int d_ = 0; d_ < NDV; ++d_) { const u32x2 lo_ = *(const LAS u32x2*)(vb + d_ * 32 * VROW), hi_ = *(const LAS u32x2*)(vb + d_ * 32 * VROW + 16); vfa[d_] = (u32x4){lo_.x, lo_.y, hi_.x, hi_.y}; }
;             }
;     ...
;             {
;                 u32x4 vfb[NDV];
;                 ATT_LOADVG(vfb, 0, 1); ATT_PVMMA(vfa, 0, 0); __builtin_amdgcn_sched_barrier(0);
;                 ATT_LOADVG(vfa, 1, 0); ATT_PVMMA(vfb, 0, 1); __builtin_amdgcn_sched_barrier(0);
;                 ATT_LOADVG(vfb, 1, 1); ATT_PVMMA(vfa, 1, 0); __builtin_amdgcn_sched_barrier(0);
;                 ATT_PVMMA(vfb, 1, 1);
;             }
.LBB0_1155:
	s_mul_i32 s24, s80, 0x4400
	v_add_u32_e32 v84, s24, v225
	v_add_u32_e32 v210, 0xc800, v84
	ds_read2_b64 v[80:83], v210 offset1:2
	v_add_u32_e32 v211, 0xd800, v84
	v_add_u32_e32 v246, 0xe800, v84
	v_add_u32_e32 v247, 0xf800, v84
	s_waitcnt lgkmcnt(0)
	v_mfma_f32_32x32x16_bf16 v[48:63], v[80:83], v[64:67], v[48:63]
	ds_read2_b64 v[80:83], v211 offset0:32 offset1:34
	s_waitcnt lgkmcnt(0)
	v_mfma_f32_32x32x16_bf16 v[32:47], v[80:83], v[64:67], v[32:47]
	ds_read2_b64 v[80:83], v246 offset0:64 offset1:66
	s_waitcnt lgkmcnt(0)
	v_mfma_f32_32x32x16_bf16 v[16:31], v[80:83], v[64:67], v[16:31]
	ds_read2_b64 v[80:83], v247 offset0:96 offset1:98
	ds_read2_b64 v[84:87], v210 offset0:4 offset1:6
	ds_read2_b64 v[88:91], v211 offset0:36 offset1:38
	ds_read2_b64 v[92:95], v246 offset0:68 offset1:70
	ds_read2_b64 v[242:245], v247 offset0:100 offset1:102
	s_waitcnt lgkmcnt(4)
	v_mfma_f32_32x32x16_bf16 v[0:15], v[80:83], v[64:67], v[0:15]
	s_waitcnt lgkmcnt(3)
	v_mfma_f32_32x32x16_bf16 v[48:63], v[84:87], v[72:75], v[48:63]
	s_waitcnt lgkmcnt(2)
	v_mfma_f32_32x32x16_bf16 v[32:47], v[88:91], v[72:75], v[32:47]
	s_waitcnt lgkmcnt(1)
	v_mfma_f32_32x32x16_bf16 v[16:31], v[92:95], v[72:75], v[16:31]
	ds_read2_b64 v[80:83], v210 offset0:8 offset1:10
	ds_read2_b64 v[84:87], v211 offset0:40 offset1:42
	ds_read2_b64 v[88:91], v246 offset0:72 offset1:74
	ds_read2_b64 v[92:95], v247 offset0:104 offset1:106
	s_waitcnt lgkmcnt(4)
	v_mfma_f32_32x32x16_bf16 v[0:15], v[242:245], v[72:75], v[0:15]
	s_waitcnt lgkmcnt(3)
	v_mfma_f32_32x32x16_bf16 v[48:63], v[80:83], v[68:71], v[48:63]
	s_waitcnt lgkmcnt(2)
	v_mfma_f32_32x32x16_bf16 v[32:47], v[84:87], v[68:71], v[32:47]
	s_waitcnt lgkmcnt(1)
	v_mfma_f32_32x32x16_bf16 v[16:31], v[88:91], v[68:71], v[16:31]
	ds_read2_b64 v[80:83], v210 offset0:12 offset1:14
	ds_read2_b64 v[84:87], v211 offset0:44 offset1:46
	ds_read2_b64 v[88:91], v246 offset0:76 offset1:78
	ds_read2_b64 v[242:245], v247 offset0:108 offset1:110
	s_waitcnt lgkmcnt(4)
	v_mfma_f32_32x32x16_bf16 v[0:15], v[92:95], v[68:71], v[0:15]
	s_waitcnt lgkmcnt(3)
	v_mfma_f32_32x32x16_bf16 v[48:63], v[80:83], v[76:79], v[48:63]
	s_waitcnt lgkmcnt(2)
	v_mfma_f32_32x32x16_bf16 v[32:47], v[84:87], v[76:79], v[32:47]
	s_waitcnt lgkmcnt(1)
	v_mfma_f32_32x32x16_bf16 v[16:31], v[88:91], v[76:79], v[16:31]
	s_waitcnt lgkmcnt(0)
	v_mfma_f32_32x32x16_bf16 v[0:15], v[242:245], v[76:79], v[0:15]
	s_andn2_b64 vcc, exec, s[22:23]
	s_cbranch_vccz .LBB0_1147
	s_branch .LBB0_1148

; __global__ void __launch_bounds__(NTHREADS) mk_fwd(Params p) {
;     __shared__ __attribute__((aligned(16))) unsigned char lds_raw[LDS_TOTAL];
	.amdhsa_kernel _Z6mk_fwd6Params
		.amdhsa_group_segment_fixed_size 131328
		.amdhsa_private_segment_fixed_size 0
		.amdhsa_kernarg_size 440
		.amdhsa_user_sgpr_count 2
		.amdhsa_user_sgpr_dispatch_ptr 0
		.amdhsa_user_sgpr_queue_ptr 0
		.amdhsa_user_sgpr_kernarg_segment_ptr 1
		.amdhsa_user_sgpr_dispatch_id 0
		.amdhsa_user_sgpr_kernarg_preload_length 0
		.amdhsa_user_sgpr_kernarg_preload_offset 0
		.amdhsa_user_sgpr_private_segment_size 0
		.amdhsa_uses_dynamic_stack 0
		.amdhsa_enable_private_segment 0
		.amdhsa_system_sgpr_workgroup_id_x 1
		.amdhsa_system_sgpr_workgroup_id_y 0
		.amdhsa_system_sgpr_workgroup_id_z 0
		.amdhsa_system_sgpr_workgroup_info 0
		.amdhsa_system_vgpr_workitem_id 2
		.amdhsa_next_free_vgpr 255
		.amdhsa_next_free_sgpr 98
		.amdhsa_accum_offset 256
		.amdhsa_reserve_vcc 1
		.amdhsa_float_round_mode_32 0
		.amdhsa_float_round_mode_16_64 0
		.amdhsa_float_denorm_mode_32 3
		.amdhsa_float_denorm_mode_16_64 3
		.amdhsa_dx10_clamp 1
		.amdhsa_ieee_mode 1
		.amdhsa_fp16_overflow 0
		.amdhsa_tg_split 0
		.amdhsa_exception_fp_ieee_invalid_op 0
		.amdhsa_exception_fp_denorm_src 0
		.amdhsa_exception_fp_ieee_div_zero 0
		.amdhsa_exception_fp_ieee_overflow 0
		.amdhsa_exception_fp_ieee_underflow 0
		.amdhsa_exception_fp_ieee_inexact 0
		.amdhsa_exception_int_div_zero 0
	.end_amdhsa_kernel

; __global__ void __launch_bounds__(NTHREADS) mk_fwd(Params p) {
;     __shared__ __attribute__((aligned(16))) unsigned char lds_raw[LDS_TOTAL];
amdhsa.kernels:
  - .agpr_count:     0
    .args:
      - .offset:         0
        .size:           184
        .value_kind:     by_value
      - .offset:         184
        .size:           4
        .value_kind:     hidden_block_count_x
      - .offset:         188
        .size:           4
        .value_kind:     hidden_block_count_y
      - .offset:         192
        .size:           4
        .value_kind:     hidden_block_count_z
      - .offset:         196
        .size:           2
        .value_kind:     hidden_group_size_x
      - .offset:         198
        .size:           2
        .value_kind:     hidden_group_size_y
      - .offset:         200
        .size:           2
        .value_kind:     hidden_group_size_z
      - .offset:         202
        .size:           2
        .value_kind:     hidden_remainder_x
      - .offset:         204
        .size:           2
        .value_kind:     hidden_remainder_y
      - .offset:         206
        .size:           2
        .value_kind:     hidden_remainder_z
      - .offset:         224
        .size:           8
        .value_kind:     hidden_global_offset_x
      - .offset:         232
        .size:           8
        .value_kind:     hidden_global_offset_y
      - .offset:         240
        .size:           8
        .value_kind:     hidden_global_offset_z
      - .offset:         248
        .size:           2
        .value_kind:     hidden_grid_dims
      - .offset:         272
        .size:           8
        .value_kind:     hidden_multigrid_sync_arg
    .group_segment_fixed_size: 131328
    .kernarg_segment_align: 8
    .kernarg_segment_size: 440
    .language:       OpenCL C
    .language_version:
      - 2
      - 0
    .max_flat_workgroup_size: 512
    .name:           _Z6mk_fwd6Params
    .private_segment_fixed_size: 0
    .sgpr_count:     104
    .sgpr_spill_count: 2
    .symbol:         _Z6mk_fwd6Params.kd
    .uniform_work_group_size: 1
    .uses_dynamic_stack: false
    .vgpr_count:     255
    .vgpr_spill_count: 0
    .wavefront_size: 64
